# batched loads: split-K finalize partial sums + prologue hb-init row copy (8 loads in flight per row instead of serial load-wait-store)
# baseline (speedup 1.0000x reference)
.LBB0_563:
	s_mul_hi_i32 s3, s54, 0xfe03f81
	s_lshr_b32 s6, s3, 31
	s_ashr_i32 s3, s3, 7
	s_add_i32 s3, s3, s6
	s_mul_i32 s6, s3, 0xfffff7f0
	s_add_i32 s12, s54, s6
	s_cmp_lt_i32 s12, 16
	s_cselect_b64 vcc, -1, 0
	s_lshl_b32 s3, s3, 11
	s_add_i32 s3, s3, -16
	s_and_b64 s[6:7], vcc, exec
	s_cselect_b32 s3, 0, s3
	s_add_i32 s6, s12, s3
	s_ashr_i32 s7, s6, 31
	s_lshl_b64 s[6:7], s[6:7], 13
	s_waitcnt lgkmcnt(0)
	v_cndmask_b32_e32 v7, v3, v5, vcc
	v_cndmask_b32_e32 v6, v2, v4, vcc
	s_cmpk_lt_i32 s54, 0x4080
	v_lshl_add_u64 v[40:41], v[6:7], 0, s[6:7]
	s_cselect_b64 s[12:13], -1, 0
	s_cmpk_gt_i32 s54, 0x407f
	v_lshlrev_b32_e32 v0, 2, v74
	v_mov_b32_e32 v10, 0
	v_mov_b32_e32 v11, 0
	v_mov_b32_e32 v12, 0
	v_mov_b32_e32 v13, 0
	v_mov_b32_e32 v6, 0
	v_mov_b32_e32 v7, 0
	v_mov_b32_e32 v8, 0
	v_mov_b32_e32 v9, 0
	v_mov_b32_e32 v18, 0
	v_mov_b32_e32 v19, 0
	v_mov_b32_e32 v20, 0
	v_mov_b32_e32 v21, 0
	v_mov_b32_e32 v14, 0
	v_mov_b32_e32 v15, 0
	v_mov_b32_e32 v16, 0
	v_mov_b32_e32 v17, 0
	v_mov_b32_e32 v26, 0
	v_mov_b32_e32 v27, 0
	v_mov_b32_e32 v28, 0
	v_mov_b32_e32 v29, 0
	v_mov_b32_e32 v22, 0
	v_mov_b32_e32 v23, 0
	v_mov_b32_e32 v24, 0
	v_mov_b32_e32 v25, 0
	v_mov_b32_e32 v34, 0
	v_mov_b32_e32 v35, 0
	v_mov_b32_e32 v36, 0
	v_mov_b32_e32 v37, 0
	v_mov_b32_e32 v30, 0
	v_mov_b32_e32 v31, 0
	v_mov_b32_e32 v32, 0
	v_mov_b32_e32 v33, 0
	s_cbranch_scc1 .Lmy_hb_proc
	v_readfirstlane_b32 s6, v40
	v_readfirstlane_b32 s7, v41
	s_nop 4
	global_load_dwordx4 v[10:13], v0, s[6:7] nt
	global_load_dwordx4 v[6:9], v0, s[6:7] offset:1024 nt
	global_load_dwordx4 v[18:21], v0, s[6:7] offset:2048 nt
	global_load_dwordx4 v[14:17], v0, s[6:7] offset:3072 nt
	s_add_u32 s6, s6, 0x1000
	s_addc_u32 s7, s7, 0
	global_load_dwordx4 v[26:29], v0, s[6:7] nt
	global_load_dwordx4 v[22:25], v0, s[6:7] offset:1024 nt
	global_load_dwordx4 v[34:37], v0, s[6:7] offset:2048 nt
	global_load_dwordx4 v[30:33], v0, s[6:7] offset:3072 nt
.Lmy_hb_proc:
	s_waitcnt vmcnt(0)
	v_cvt_pk_bf16_f32 v100, v10, v11
	v_cvt_pk_bf16_f32 v101, v12, v13
	v_cvt_pk_bf16_f32 v102, v6, v7
	v_cvt_pk_bf16_f32 v103, v8, v9
	v_cvt_pk_bf16_f32 v104, v18, v19
	v_cvt_pk_bf16_f32 v105, v20, v21
	v_cvt_pk_bf16_f32 v106, v14, v15
	v_cvt_pk_bf16_f32 v107, v16, v17
	v_cvt_pk_bf16_f32 v108, v26, v27
	v_cvt_pk_bf16_f32 v109, v28, v29
	v_cvt_pk_bf16_f32 v110, v22, v23
	v_cvt_pk_bf16_f32 v111, v24, v25
	v_cvt_pk_bf16_f32 v112, v34, v35
	v_cvt_pk_bf16_f32 v113, v36, v37
	v_cvt_pk_bf16_f32 v114, v30, v31
	v_cvt_pk_bf16_f32 v115, v32, v33
	global_store_dwordx2 v[38:39], v[100:101], off offset:-2048
	global_store_dwordx2 v[38:39], v[102:103], off offset:-1536
	global_store_dwordx2 v[38:39], v[104:105], off offset:-1024
	global_store_dwordx2 v[38:39], v[106:107], off offset:-512
	global_store_dwordx2 v[38:39], v[108:109], off
	global_store_dwordx2 v[38:39], v[110:111], off offset:512
	global_store_dwordx2 v[38:39], v[112:113], off offset:1024
	global_store_dwordx2 v[38:39], v[114:115], off offset:1536
	v_mul_f32_e32 v0, v11, v11
	v_mul_f32_e32 v7, v7, v7
	v_fmac_f32_e32 v0, v10, v10
	v_mul_f32_e32 v10, v13, v13
	v_fmac_f32_e32 v7, v6, v6
	v_mul_f32_e32 v6, v9, v9
	v_fmac_f32_e32 v10, v12, v12
	v_fmac_f32_e32 v6, v8, v8
	v_add_f32_e32 v0, v0, v10
	v_add_f32_e32 v6, v7, v6
	v_add_f32_e32 v0, v0, v6
	v_mul_f32_e32 v6, v19, v19
	v_mul_f32_e32 v7, v21, v21
	v_fmac_f32_e32 v6, v18, v18
	v_fmac_f32_e32 v7, v20, v20
	v_add_f32_e32 v6, v6, v7
	v_add_f32_e32 v0, v0, v6
	v_mul_f32_e32 v6, v15, v15
	v_mul_f32_e32 v7, v17, v17
	v_fmac_f32_e32 v6, v14, v14
	v_fmac_f32_e32 v7, v16, v16
	v_add_f32_e32 v6, v6, v7
	v_add_f32_e32 v0, v0, v6
	v_mul_f32_e32 v6, v27, v27
	v_mul_f32_e32 v7, v29, v29
	v_fmac_f32_e32 v6, v26, v26
	v_fmac_f32_e32 v7, v28, v28
	v_add_f32_e32 v6, v6, v7
	v_add_f32_e32 v0, v0, v6
	v_mul_f32_e32 v6, v23, v23
	v_mul_f32_e32 v7, v25, v25
	v_fmac_f32_e32 v6, v22, v22
	v_fmac_f32_e32 v7, v24, v24
	v_add_f32_e32 v6, v6, v7
	v_add_f32_e32 v0, v0, v6
	v_mul_f32_e32 v6, v35, v35
	v_mul_f32_e32 v7, v37, v37
	v_fmac_f32_e32 v6, v34, v34
	v_fmac_f32_e32 v7, v36, v36
	v_add_f32_e32 v6, v6, v7
	v_add_f32_e32 v0, v0, v6
	v_mul_f32_e32 v6, v31, v31
	v_mul_f32_e32 v7, v33, v33
	v_fmac_f32_e32 v6, v30, v30
	v_fmac_f32_e32 v7, v32, v32
	v_add_f32_e32 v6, v6, v7
	v_add_f32_e32 v0, v0, v6
	ds_bpermute_b32 v6, v42, v0
	s_waitcnt lgkmcnt(0)
	v_add_f32_e32 v0, v0, v6
	ds_bpermute_b32 v6, v43, v0
	s_waitcnt lgkmcnt(0)
	v_add_f32_e32 v0, v0, v6
	ds_bpermute_b32 v6, v44, v0
	s_waitcnt lgkmcnt(0)
	v_add_f32_e32 v0, v0, v6
	ds_bpermute_b32 v6, v45, v0
	s_waitcnt lgkmcnt(0)
	v_add_f32_e32 v0, v0, v6
	ds_bpermute_b32 v6, v46, v0
	s_waitcnt lgkmcnt(0)
	v_add_f32_e32 v0, v0, v6
	ds_bpermute_b32 v6, v47, v0
	s_and_saveexec_b64 s[6:7], s[4:5]
	s_cbranch_execz .LBB0_562
	s_waitcnt lgkmcnt(0)
	v_add_f32_e32 v0, v0, v6
	global_store_dword v1, v0, s[0:1]
	s_branch .LBB0_562
